# v64 + O2 epilogue: u / q_lat / kv_lat rows staged through wave-private LDS and stored as 16-byte row chunks
# speedup vs baseline: 1.0020x; 1.0020x over previous
.LBB0_295:
	s_andn2_saveexec_b64 s[6:7], s[6:7]
	s_cbranch_execz .LBB0_331
	v_lshlrev_b64 v[78:79], 9, v[144:145]
	v_lshlrev_b64 v[76:77], 8, v[144:145]
	v_lshl_add_u64 v[78:79], s[60:61], 0, v[78:79]
	v_ashrrev_i32_e32 v147, 31, v146
	v_lshl_add_u64 v[124:125], v[146:147], 1, v[78:79]
	v_cvt_pk_bf16_f32 v184, v134, v135
	v_cvt_pk_bf16_f32 v185, v136, v137
	v_lshl_add_u64 v[76:77], v[76:77], 2, s[68:69]
	v_and_b32_e32 v230, 31, v155
	v_bfe_u32 v231, v155, 5, 1
	v_lshrrev_b32_e32 v232, 6, v155
	v_lshrrev_b32_e32 v233, 1, v232
	v_and_b32_e32 v233, v233, v232
	v_lshrrev_b32_e32 v234, 2, v232
	v_and_b32_e32 v233, v233, v234
	v_mul_u32_u24_e32 v232, 0x2200, v232
	v_mul_u32_u24_e32 v233, 0x11200, v233
	v_add_u32_e32 v232, v232, v233
	v_mul_u32_u24_e32 v238, 0x110, v230
	v_add_u32_e32 v238, v238, v232
	v_lshl_add_u32 v238, v231, 3, v238
	v_bfe_u32 v234, v155, 4, 2
	v_and_b32_e32 v235, 15, v155
	v_mul_u32_u24_e32 v239, 0x110, v234
	v_add_u32_e32 v239, v239, v232
	v_lshl_add_u32 v239, v235, 4, v239
	v_sub_u32_e32 v236, v234, v230
	v_mul_i32_i24_e32 v236, 0x200, v236
	v_lshl_add_u32 v236, v235, 4, v236
	v_lshlrev_b32_e32 v237, 3, v231
	v_sub_u32_e32 v246, v236, v237
	v_ashrrev_i32_e32 v247, 31, v246
	v_lshl_add_u64 v[244:245], v[124:125], 0, v[246:247]
	v_mov_b32_e32 v246, 0x800
	v_mov_b32_e32 v247, 0
	ds_write_b64 v238, v[184:185]
	s_and_saveexec_b64 s[8:9], s[40:41]
	s_cbranch_execz .LBB0_298
	v_lshl_add_u64 v[124:125], v[146:147], 2, v[76:77]
	global_store_dwordx4 v[124:125], v[134:137], off
.LBB0_298:
	s_or_b64 exec, exec, s[8:9]
	v_or_b32_e32 v124, 8, v146
	v_ashrrev_i32_e32 v125, 31, v124
	v_lshl_add_u64 v[134:135], v[124:125], 1, v[78:79]
	v_cvt_pk_bf16_f32 v136, v130, v131
	v_cvt_pk_bf16_f32 v137, v132, v133
	ds_write_b64 v238, v[136:137] offset:16
	s_and_saveexec_b64 s[8:9], s[40:41]
	s_cbranch_execz .LBB0_300
	v_lshl_add_u64 v[124:125], v[124:125], 2, v[76:77]
	global_store_dwordx4 v[124:125], v[130:133], off
.LBB0_300:
	s_or_b64 exec, exec, s[8:9]
	v_or_b32_e32 v124, 16, v146
	v_ashrrev_i32_e32 v125, 31, v124
	v_lshl_add_u64 v[130:131], v[124:125], 1, v[78:79]
	v_cvt_pk_bf16_f32 v132, v112, v113
	v_cvt_pk_bf16_f32 v133, v114, v115
	ds_write_b64 v238, v[132:133] offset:32
	s_and_saveexec_b64 s[8:9], s[40:41]
	s_cbranch_execz .LBB0_302
	v_lshl_add_u64 v[124:125], v[124:125], 2, v[76:77]
	global_store_dwordx4 v[124:125], v[112:115], off
.LBB0_302:
	s_or_b64 exec, exec, s[8:9]
	s_nop 0
	v_or_b32_e32 v112, 24, v146
	v_ashrrev_i32_e32 v113, 31, v112
	v_lshl_add_u64 v[114:115], v[112:113], 1, v[78:79]
	v_cvt_pk_bf16_f32 v124, v116, v117
	v_cvt_pk_bf16_f32 v125, v118, v119
	ds_write_b64 v238, v[124:125] offset:48
	s_and_saveexec_b64 s[8:9], s[40:41]
	s_cbranch_execz .LBB0_304
	v_lshl_add_u64 v[112:113], v[112:113], 2, v[76:77]
	global_store_dwordx4 v[112:113], v[116:119], off
.LBB0_304:
	s_or_b64 exec, exec, s[8:9]
	v_or_b32_e32 v112, 32, v146
	v_ashrrev_i32_e32 v113, 31, v112
	v_lshl_add_u64 v[114:115], v[112:113], 1, v[78:79]
	v_cvt_pk_bf16_f32 v116, v96, v97
	v_cvt_pk_bf16_f32 v117, v98, v99
	ds_write_b64 v238, v[116:117] offset:64
	s_and_saveexec_b64 s[8:9], s[40:41]
	s_cbranch_execz .LBB0_306
	v_lshl_add_u64 v[112:113], v[112:113], 2, v[76:77]
	global_store_dwordx4 v[112:113], v[96:99], off
.LBB0_306:
	s_or_b64 exec, exec, s[8:9]
	s_nop 0
	v_or_b32_e32 v96, 40, v146
	v_ashrrev_i32_e32 v97, 31, v96
	v_lshl_add_u64 v[98:99], v[96:97], 1, v[78:79]
	v_cvt_pk_bf16_f32 v112, v120, v121
	v_cvt_pk_bf16_f32 v113, v122, v123
	ds_write_b64 v238, v[112:113] offset:80
	s_and_saveexec_b64 s[8:9], s[40:41]
	s_cbranch_execz .LBB0_308
	v_lshl_add_u64 v[96:97], v[96:97], 2, v[76:77]
	global_store_dwordx4 v[96:97], v[120:123], off
.LBB0_308:
	s_or_b64 exec, exec, s[8:9]
	v_or_b32_e32 v96, 48, v146
	v_ashrrev_i32_e32 v97, 31, v96
	v_lshl_add_u64 v[98:99], v[96:97], 1, v[78:79]
	v_cvt_pk_bf16_f32 v112, v100, v101
	v_cvt_pk_bf16_f32 v113, v102, v103
	ds_write_b64 v238, v[112:113] offset:96
	s_and_saveexec_b64 s[8:9], s[40:41]
	s_cbranch_execz .LBB0_310
	v_lshl_add_u64 v[96:97], v[96:97], 2, v[76:77]
	global_store_dwordx4 v[96:97], v[100:103], off
.LBB0_310:
	s_or_b64 exec, exec, s[8:9]
	v_or_b32_e32 v96, 56, v146
	v_ashrrev_i32_e32 v97, 31, v96
	v_lshl_add_u64 v[98:99], v[96:97], 1, v[78:79]
	v_cvt_pk_bf16_f32 v100, v104, v105
	v_cvt_pk_bf16_f32 v101, v106, v107
	ds_write_b64 v238, v[100:101] offset:112
	s_and_saveexec_b64 s[8:9], s[40:41]
	s_cbranch_execz .LBB0_312
	v_lshl_add_u64 v[96:97], v[96:97], 2, v[76:77]
	global_store_dwordx4 v[96:97], v[104:107], off
.LBB0_312:
	s_or_b64 exec, exec, s[8:9]
	v_or_b32_e32 v96, 64, v146
	v_ashrrev_i32_e32 v97, 31, v96
	v_lshl_add_u64 v[98:99], v[96:97], 1, v[78:79]
	v_cvt_pk_bf16_f32 v100, v80, v81
	v_cvt_pk_bf16_f32 v101, v82, v83
	ds_write_b64 v238, v[100:101] offset:128
	s_and_saveexec_b64 s[8:9], s[40:41]
	s_cbranch_execz .LBB0_314
	v_lshl_add_u64 v[96:97], v[96:97], 2, v[76:77]
	global_store_dwordx4 v[96:97], v[80:83], off
.LBB0_314:
	s_or_b64 exec, exec, s[8:9]
	s_nop 0
	v_or_b32_e32 v80, 0x48, v146
	v_ashrrev_i32_e32 v81, 31, v80
	v_lshl_add_u64 v[82:83], v[80:81], 1, v[78:79]
	v_cvt_pk_bf16_f32 v96, v108, v109
	v_cvt_pk_bf16_f32 v97, v110, v111
	ds_write_b64 v238, v[96:97] offset:144
	s_and_saveexec_b64 s[8:9], s[40:41]
	s_cbranch_execz .LBB0_316
	v_lshl_add_u64 v[80:81], v[80:81], 2, v[76:77]
	global_store_dwordx4 v[80:81], v[108:111], off
.LBB0_316:
	s_or_b64 exec, exec, s[8:9]
	v_or_b32_e32 v80, 0x50, v146
	v_ashrrev_i32_e32 v81, 31, v80
	v_lshl_add_u64 v[82:83], v[80:81], 1, v[78:79]
	v_cvt_pk_bf16_f32 v96, v84, v85
	v_cvt_pk_bf16_f32 v97, v86, v87
	ds_write_b64 v238, v[96:97] offset:160
	s_and_saveexec_b64 s[8:9], s[40:41]
	s_cbranch_execz .LBB0_318
	v_lshl_add_u64 v[80:81], v[80:81], 2, v[76:77]
	global_store_dwordx4 v[80:81], v[84:87], off
.LBB0_318:
	s_or_b64 exec, exec, s[8:9]
	v_or_b32_e32 v80, 0x58, v146
	v_ashrrev_i32_e32 v81, 31, v80
	v_lshl_add_u64 v[82:83], v[80:81], 1, v[78:79]
	v_cvt_pk_bf16_f32 v84, v88, v89
	v_cvt_pk_bf16_f32 v85, v90, v91
	ds_write_b64 v238, v[84:85] offset:176
	s_and_saveexec_b64 s[8:9], s[40:41]
	s_cbranch_execz .LBB0_320
	v_lshl_add_u64 v[80:81], v[80:81], 2, v[76:77]
	global_store_dwordx4 v[80:81], v[88:91], off
.LBB0_320:
	s_or_b64 exec, exec, s[8:9]
	v_or_b32_e32 v80, 0x60, v146
	v_ashrrev_i32_e32 v81, 31, v80
	v_lshl_add_u64 v[82:83], v[80:81], 1, v[78:79]
	v_cvt_pk_bf16_f32 v84, v64, v65
	v_cvt_pk_bf16_f32 v85, v66, v67
	ds_write_b64 v238, v[84:85] offset:192
	s_and_saveexec_b64 s[8:9], s[40:41]
	s_cbranch_execz .LBB0_322
	v_lshl_add_u64 v[80:81], v[80:81], 2, v[76:77]
	global_store_dwordx4 v[80:81], v[64:67], off
.LBB0_322:
	s_or_b64 exec, exec, s[8:9]
	s_nop 0
	v_or_b32_e32 v64, 0x68, v146
	v_ashrrev_i32_e32 v65, 31, v64
	v_lshl_add_u64 v[66:67], v[64:65], 1, v[78:79]
	v_cvt_pk_bf16_f32 v80, v92, v93
	v_cvt_pk_bf16_f32 v81, v94, v95
	ds_write_b64 v238, v[80:81] offset:208
	s_and_saveexec_b64 s[8:9], s[40:41]
	s_cbranch_execz .LBB0_324
	v_lshl_add_u64 v[64:65], v[64:65], 2, v[76:77]
	global_store_dwordx4 v[64:65], v[92:95], off
.LBB0_324:
	s_or_b64 exec, exec, s[8:9]
	v_or_b32_e32 v64, 0x70, v146
	v_ashrrev_i32_e32 v65, 31, v64
	v_lshl_add_u64 v[66:67], v[64:65], 1, v[78:79]
	v_cvt_pk_bf16_f32 v80, v68, v69
	v_cvt_pk_bf16_f32 v81, v70, v71
	ds_write_b64 v238, v[80:81] offset:224
	s_and_saveexec_b64 s[8:9], s[40:41]
	s_cbranch_execz .LBB0_326
	v_lshl_add_u64 v[64:65], v[64:65], 2, v[76:77]
	global_store_dwordx4 v[64:65], v[68:71], off
.LBB0_326:
	s_or_b64 exec, exec, s[8:9]
	v_or_b32_e32 v64, 0x78, v146
	v_ashrrev_i32_e32 v65, 31, v64
	v_lshl_add_u64 v[66:67], v[64:65], 1, v[78:79]
	v_cvt_pk_bf16_f32 v68, v72, v73
	v_cvt_pk_bf16_f32 v69, v74, v75
	ds_write_b64 v238, v[68:69] offset:240
	s_waitcnt lgkmcnt(0)
	ds_read_b128 v[230:233], v239
	ds_read_b128 v[234:237], v239 offset:1088
	s_waitcnt lgkmcnt(1)
	global_store_dwordx4 v[244:245], v[230:233], off
	v_lshl_add_u64 v[244:245], v[244:245], 0, v[246:247]
	s_nop 4
	ds_read_b128 v[230:233], v239 offset:2176
	s_waitcnt lgkmcnt(1)
	global_store_dwordx4 v[244:245], v[234:237], off
	v_lshl_add_u64 v[244:245], v[244:245], 0, v[246:247]
	s_nop 4
	ds_read_b128 v[234:237], v239 offset:3264
	s_waitcnt lgkmcnt(1)
	global_store_dwordx4 v[244:245], v[230:233], off
	v_lshl_add_u64 v[244:245], v[244:245], 0, v[246:247]
	s_nop 4
	ds_read_b128 v[230:233], v239 offset:4352
	s_waitcnt lgkmcnt(1)
	global_store_dwordx4 v[244:245], v[234:237], off
	v_lshl_add_u64 v[244:245], v[244:245], 0, v[246:247]
	s_nop 4
	ds_read_b128 v[234:237], v239 offset:5440
	s_waitcnt lgkmcnt(1)
	global_store_dwordx4 v[244:245], v[230:233], off
	v_lshl_add_u64 v[244:245], v[244:245], 0, v[246:247]
	s_nop 4
	ds_read_b128 v[230:233], v239 offset:6528
	s_waitcnt lgkmcnt(1)
	global_store_dwordx4 v[244:245], v[234:237], off
	v_lshl_add_u64 v[244:245], v[244:245], 0, v[246:247]
	s_nop 4
	ds_read_b128 v[234:237], v239 offset:7616
	s_waitcnt lgkmcnt(1)
	global_store_dwordx4 v[244:245], v[230:233], off
	v_lshl_add_u64 v[244:245], v[244:245], 0, v[246:247]
	s_waitcnt lgkmcnt(0)
	global_store_dwordx4 v[244:245], v[234:237], off
	s_and_saveexec_b64 s[8:9], s[40:41]
	s_cbranch_execz .LBB0_328
	v_lshl_add_u64 v[64:65], v[64:65], 2, v[76:77]
	global_store_dwordx4 v[64:65], v[72:75], off

.LBB0_332:
	s_andn2_saveexec_b64 s[4:5], s[4:5]
	s_cbranch_execz .LBB0_336
	v_mov_b64_e32 v[76:77], s[58:59]
	v_mad_i64_i32 v[76:77], s[6:7], v144, s34, v[76:77]
	v_lshl_add_u64 v[76:77], v[128:129], 1, v[76:77]
	v_lshlrev_b32_e32 v78, 1, v181
	v_mov_b32_e32 v79, v129
	v_lshl_add_u64 v[76:77], v[76:77], 0, v[78:79]
	v_cvt_pk_bf16_f32 v78, v130, v131
	v_cvt_pk_bf16_f32 v79, v132, v133
	v_and_b32_e32 v230, 31, v155
	v_bfe_u32 v231, v155, 5, 1
	v_lshrrev_b32_e32 v232, 6, v155
	v_lshrrev_b32_e32 v233, 1, v232
	v_and_b32_e32 v233, v233, v232
	v_lshrrev_b32_e32 v234, 2, v232
	v_and_b32_e32 v233, v233, v234
	v_mul_u32_u24_e32 v232, 0x2200, v232
	v_mul_u32_u24_e32 v233, 0x11200, v233
	v_add_u32_e32 v232, v232, v233
	v_mul_u32_u24_e32 v238, 0x110, v230
	v_add_u32_e32 v238, v238, v232
	v_lshl_add_u32 v238, v231, 3, v238
	v_bfe_u32 v234, v155, 4, 2
	v_and_b32_e32 v235, 15, v155
	v_mul_u32_u24_e32 v239, 0x110, v234
	v_add_u32_e32 v239, v239, v232
	v_lshl_add_u32 v239, v235, 4, v239
	v_sub_u32_e32 v236, v234, v230
	v_mul_i32_i24_e32 v236, 0x300, v236
	v_lshl_add_u32 v236, v235, 4, v236
	v_lshlrev_b32_e32 v237, 3, v231
	v_sub_u32_e32 v246, v236, v237
	v_add_u32_e32 v246, 0xfffffc00, v246
	v_ashrrev_i32_e32 v247, 31, v246
	v_lshl_add_u64 v[244:245], v[76:77], 0, v[246:247]
	v_mov_b32_e32 v246, 0xc00
	v_mov_b32_e32 v247, 0
	ds_write_b64 v238, v[78:79] offset:16
	v_cvt_pk_bf16_f32 v78, v112, v113
	v_cvt_pk_bf16_f32 v79, v114, v115
	ds_write_b64 v238, v[78:79] offset:32
	v_cvt_pk_bf16_f32 v78, v116, v117
	v_cvt_pk_bf16_f32 v79, v118, v119
	ds_write_b64 v238, v[78:79] offset:48
	v_cvt_pk_bf16_f32 v78, v96, v97
	v_cvt_pk_bf16_f32 v79, v98, v99
	ds_write_b64 v238, v[78:79] offset:64
	v_cvt_pk_bf16_f32 v78, v120, v121
	v_cvt_pk_bf16_f32 v79, v122, v123
	ds_write_b64 v238, v[78:79] offset:80
	v_cvt_pk_bf16_f32 v78, v100, v101
	v_cvt_pk_bf16_f32 v79, v102, v103
	ds_write_b64 v238, v[78:79] offset:96
	v_cvt_pk_bf16_f32 v78, v104, v105
	v_cvt_pk_bf16_f32 v79, v106, v107
	ds_write_b64 v238, v[78:79] offset:112
	v_cvt_pk_bf16_f32 v78, v80, v81
	v_cvt_pk_bf16_f32 v79, v82, v83
	v_cvt_pk_bf16_f32 v64, v64, v65
	v_cvt_pk_bf16_f32 v65, v66, v67
	ds_write_b64 v238, v[78:79] offset:128
	v_cvt_pk_bf16_f32 v78, v108, v109
	v_cvt_pk_bf16_f32 v79, v110, v111
	ds_write_b64 v238, v[64:65] offset:192
	v_cvt_pk_bf16_f32 v64, v92, v93
	v_cvt_pk_bf16_f32 v65, v94, v95
	ds_write_b64 v238, v[78:79] offset:144
	v_cvt_pk_bf16_f32 v78, v84, v85
	v_cvt_pk_bf16_f32 v79, v86, v87
	ds_write_b64 v238, v[64:65] offset:208
	v_cvt_pk_bf16_f32 v64, v68, v69
	v_cvt_pk_bf16_f32 v65, v70, v71
	v_cvt_pk_bf16_f32 v124, v134, v135
	v_cvt_pk_bf16_f32 v125, v136, v137
	ds_write_b64 v238, v[78:79] offset:160
	v_cvt_pk_bf16_f32 v78, v88, v89
	v_cvt_pk_bf16_f32 v79, v90, v91
	ds_write_b64 v238, v[64:65] offset:224
	v_cvt_pk_bf16_f32 v64, v72, v73
	v_cvt_pk_bf16_f32 v65, v74, v75
	ds_write_b64 v238, v[124:125]
	ds_write_b64 v238, v[78:79] offset:176
	ds_write_b64 v238, v[64:65] offset:240
	s_waitcnt lgkmcnt(0)
	ds_read_b128 v[230:233], v239
	ds_read_b128 v[234:237], v239 offset:1088
	s_waitcnt lgkmcnt(1)
	global_store_dwordx4 v[244:245], v[230:233], off
	v_lshl_add_u64 v[244:245], v[244:245], 0, v[246:247]
	s_nop 4
	ds_read_b128 v[230:233], v239 offset:2176
	s_waitcnt lgkmcnt(1)
	global_store_dwordx4 v[244:245], v[234:237], off
	v_lshl_add_u64 v[244:245], v[244:245], 0, v[246:247]
	s_nop 4
	ds_read_b128 v[234:237], v239 offset:3264
	s_waitcnt lgkmcnt(1)
	global_store_dwordx4 v[244:245], v[230:233], off
	v_lshl_add_u64 v[244:245], v[244:245], 0, v[246:247]
	s_nop 4
	ds_read_b128 v[230:233], v239 offset:4352
	s_waitcnt lgkmcnt(1)
	global_store_dwordx4 v[244:245], v[234:237], off
	v_lshl_add_u64 v[244:245], v[244:245], 0, v[246:247]
	s_nop 4
	ds_read_b128 v[234:237], v239 offset:5440
	s_waitcnt lgkmcnt(1)
	global_store_dwordx4 v[244:245], v[230:233], off
	v_lshl_add_u64 v[244:245], v[244:245], 0, v[246:247]
	s_nop 4
	ds_read_b128 v[230:233], v239 offset:6528
	s_waitcnt lgkmcnt(1)
	global_store_dwordx4 v[244:245], v[234:237], off
	v_lshl_add_u64 v[244:245], v[244:245], 0, v[246:247]
	s_nop 4
	ds_read_b128 v[234:237], v239 offset:7616
	s_waitcnt lgkmcnt(1)
	global_store_dwordx4 v[244:245], v[230:233], off
	v_lshl_add_u64 v[244:245], v[244:245], 0, v[246:247]
	s_waitcnt lgkmcnt(0)
	global_store_dwordx4 v[244:245], v[234:237], off
	s_and_saveexec_b64 s[6:7], vcc
	s_cbranch_execz .LBB0_335
	v_lshl_add_u64 v[64:65], s[64:65], 0, v[150:151]
	v_lshl_add_u64 v[64:65], v[144:145], 2, v[64:65]
	global_store_dword v[64:65], v127, off

.LBB0_337:
	s_or_saveexec_b64 s[2:3], s[2:3]
	v_ashrrev_i32_e32 v153, 31, v152
	v_lshlrev_b32_e32 v76, 1, v181
	s_xor_b64 exec, exec, s[2:3]
	s_cbranch_execz .LBB0_339
	v_lshlrev_b64 v[78:79], 10, v[144:145]
	v_lshl_add_u64 v[78:79], s[56:57], 0, v[78:79]
	v_lshl_add_u64 v[78:79], v[152:153], 1, v[78:79]
	v_mov_b32_e32 v77, v129
	v_lshl_add_u64 v[78:79], v[78:79], 0, v[76:77]
	v_cvt_pk_bf16_f32 v96, v96, v97
	v_cvt_pk_bf16_f32 v97, v98, v99
	v_cvt_pk_bf16_f32 v80, v80, v81
	v_cvt_pk_bf16_f32 v81, v82, v83
	v_cvt_pk_bf16_f32 v64, v64, v65
	v_cvt_pk_bf16_f32 v65, v66, v67
	v_and_b32_e32 v230, 31, v155
	v_bfe_u32 v231, v155, 5, 1
	v_lshrrev_b32_e32 v232, 6, v155
	v_lshrrev_b32_e32 v233, 1, v232
	v_and_b32_e32 v233, v233, v232
	v_lshrrev_b32_e32 v234, 2, v232
	v_and_b32_e32 v233, v233, v234
	v_mul_u32_u24_e32 v232, 0x2200, v232
	v_mul_u32_u24_e32 v233, 0x11200, v233
	v_add_u32_e32 v232, v232, v233
	v_mul_u32_u24_e32 v238, 0x110, v230
	v_add_u32_e32 v238, v238, v232
	v_lshl_add_u32 v238, v231, 3, v238
	v_bfe_u32 v234, v155, 4, 2
	v_and_b32_e32 v235, 15, v155
	v_mul_u32_u24_e32 v239, 0x110, v234
	v_add_u32_e32 v239, v239, v232
	v_lshl_add_u32 v239, v235, 4, v239
	v_sub_u32_e32 v236, v234, v230
	v_mul_i32_i24_e32 v236, 0x400, v236
	v_lshl_add_u32 v236, v235, 4, v236
	v_lshlrev_b32_e32 v237, 3, v231
	v_sub_u32_e32 v246, v236, v237
	v_ashrrev_i32_e32 v247, 31, v246
	v_lshl_add_u64 v[244:245], v[78:79], 0, v[246:247]
	v_mov_b32_e32 v246, 0x1000
	v_mov_b32_e32 v247, 0
	ds_write_b64 v238, v[96:97] offset:64
	v_cvt_pk_bf16_f32 v96, v120, v121
	v_cvt_pk_bf16_f32 v97, v122, v123
	ds_write_b64 v238, v[80:81] offset:128
	v_cvt_pk_bf16_f32 v80, v108, v109
	v_cvt_pk_bf16_f32 v81, v110, v111
	ds_write_b64 v238, v[64:65] offset:192
	v_cvt_pk_bf16_f32 v64, v92, v93
	v_cvt_pk_bf16_f32 v65, v94, v95
	v_cvt_pk_bf16_f32 v124, v134, v135
	v_cvt_pk_bf16_f32 v125, v136, v137
	v_cvt_pk_bf16_f32 v112, v112, v113
	v_cvt_pk_bf16_f32 v113, v114, v115
	ds_write_b64 v238, v[96:97] offset:80
	v_cvt_pk_bf16_f32 v96, v100, v101
	v_cvt_pk_bf16_f32 v97, v102, v103
	ds_write_b64 v238, v[80:81] offset:144
	v_cvt_pk_bf16_f32 v80, v84, v85
	v_cvt_pk_bf16_f32 v81, v86, v87
	ds_write_b64 v238, v[64:65] offset:208
	v_cvt_pk_bf16_f32 v64, v68, v69
	v_cvt_pk_bf16_f32 v65, v70, v71
	ds_write_b64 v238, v[124:125]
	v_cvt_pk_bf16_f32 v124, v130, v131
	v_cvt_pk_bf16_f32 v125, v132, v133
	ds_write_b64 v238, v[112:113] offset:32
	v_cvt_pk_bf16_f32 v112, v116, v117
	v_cvt_pk_bf16_f32 v113, v118, v119
	ds_write_b64 v238, v[96:97] offset:96
	v_cvt_pk_bf16_f32 v96, v104, v105
	v_cvt_pk_bf16_f32 v97, v106, v107
	ds_write_b64 v238, v[80:81] offset:160
	v_cvt_pk_bf16_f32 v80, v88, v89
	v_cvt_pk_bf16_f32 v81, v90, v91
	ds_write_b64 v238, v[64:65] offset:224
	v_cvt_pk_bf16_f32 v64, v72, v73
	v_cvt_pk_bf16_f32 v65, v74, v75
	ds_write_b64 v238, v[124:125] offset:16
	ds_write_b64 v238, v[112:113] offset:48
	ds_write_b64 v238, v[96:97] offset:112
	ds_write_b64 v238, v[80:81] offset:176
	ds_write_b64 v238, v[64:65] offset:240
	s_waitcnt lgkmcnt(0)
	ds_read_b128 v[230:233], v239
	ds_read_b128 v[234:237], v239 offset:1088
	s_waitcnt lgkmcnt(1)
	global_store_dwordx4 v[244:245], v[230:233], off
	v_lshl_add_u64 v[244:245], v[244:245], 0, v[246:247]
	s_nop 4
	ds_read_b128 v[230:233], v239 offset:2176
	s_waitcnt lgkmcnt(1)
	global_store_dwordx4 v[244:245], v[234:237], off
	v_lshl_add_u64 v[244:245], v[244:245], 0, v[246:247]
	s_nop 4
	ds_read_b128 v[234:237], v239 offset:3264
	s_waitcnt lgkmcnt(1)
	global_store_dwordx4 v[244:245], v[230:233], off
	v_lshl_add_u64 v[244:245], v[244:245], 0, v[246:247]
	s_nop 4
	ds_read_b128 v[230:233], v239 offset:4352
	s_waitcnt lgkmcnt(1)
	global_store_dwordx4 v[244:245], v[234:237], off
	v_lshl_add_u64 v[244:245], v[244:245], 0, v[246:247]
	s_nop 4
	ds_read_b128 v[234:237], v239 offset:5440
	s_waitcnt lgkmcnt(1)
	global_store_dwordx4 v[244:245], v[230:233], off
	v_lshl_add_u64 v[244:245], v[244:245], 0, v[246:247]
	s_nop 4
	ds_read_b128 v[230:233], v239 offset:6528
	s_waitcnt lgkmcnt(1)
	global_store_dwordx4 v[244:245], v[234:237], off
	v_lshl_add_u64 v[244:245], v[244:245], 0, v[246:247]
	s_nop 4
	ds_read_b128 v[234:237], v239 offset:7616
	s_waitcnt lgkmcnt(1)
	global_store_dwordx4 v[244:245], v[230:233], off
	v_lshl_add_u64 v[244:245], v[244:245], 0, v[246:247]
	s_waitcnt lgkmcnt(0)
	global_store_dwordx4 v[244:245], v[234:237], off

.LBB0_351:
	s_andn2_saveexec_b64 s[0:1], s[0:1]
	s_cbranch_execz .LBB0_387
	v_lshlrev_b64 v[14:15], 9, v[72:73]
	v_lshlrev_b64 v[12:13], 8, v[72:73]
	v_lshl_add_u64 v[14:15], s[60:61], 0, v[14:15]
	v_ashrrev_i32_e32 v147, 31, v146
	v_lshl_add_u64 v[60:61], v[146:147], 1, v[14:15]
	v_cvt_pk_bf16_f32 v72, v68, v69
	v_cvt_pk_bf16_f32 v73, v70, v71
	v_lshl_add_u64 v[12:13], v[12:13], 2, s[68:69]
	v_and_b32_e32 v230, 31, v155
	v_bfe_u32 v231, v155, 5, 1
	v_lshrrev_b32_e32 v232, 6, v155
	v_lshrrev_b32_e32 v233, 1, v232
	v_and_b32_e32 v233, v233, v232
	v_lshrrev_b32_e32 v234, 2, v232
	v_and_b32_e32 v233, v233, v234
	v_mul_u32_u24_e32 v232, 0x2200, v232
	v_mul_u32_u24_e32 v233, 0x11200, v233
	v_add_u32_e32 v232, v232, v233
	v_mul_u32_u24_e32 v238, 0x110, v230
	v_add_u32_e32 v238, v238, v232
	v_lshl_add_u32 v238, v231, 3, v238
	v_bfe_u32 v234, v155, 4, 2
	v_and_b32_e32 v235, 15, v155
	v_mul_u32_u24_e32 v239, 0x110, v234
	v_add_u32_e32 v239, v239, v232
	v_lshl_add_u32 v239, v235, 4, v239
	v_sub_u32_e32 v236, v234, v230
	v_mul_i32_i24_e32 v236, 0x200, v236
	v_lshl_add_u32 v236, v235, 4, v236
	v_lshlrev_b32_e32 v237, 3, v231
	v_sub_u32_e32 v246, v236, v237
	v_ashrrev_i32_e32 v247, 31, v246
	v_lshl_add_u64 v[244:245], v[60:61], 0, v[246:247]
	v_mov_b32_e32 v246, 0x800
	v_mov_b32_e32 v247, 0
	ds_write_b64 v238, v[72:73]
	s_and_saveexec_b64 s[6:7], s[36:37]
	s_cbranch_execz .LBB0_354
	v_lshl_add_u64 v[60:61], v[146:147], 2, v[12:13]
	global_store_dwordx4 v[60:61], v[68:71], off
.LBB0_354:
	s_or_b64 exec, exec, s[6:7]
	v_or_b32_e32 v60, 8, v146
	v_ashrrev_i32_e32 v61, 31, v60
	v_lshl_add_u64 v[68:69], v[60:61], 1, v[14:15]
	v_cvt_pk_bf16_f32 v70, v64, v65
	v_cvt_pk_bf16_f32 v71, v66, v67
	ds_write_b64 v238, v[70:71] offset:16
	s_and_saveexec_b64 s[6:7], s[36:37]
	s_cbranch_execz .LBB0_356
	v_lshl_add_u64 v[60:61], v[60:61], 2, v[12:13]
	global_store_dwordx4 v[60:61], v[64:67], off
.LBB0_356:
	s_or_b64 exec, exec, s[6:7]
	v_or_b32_e32 v60, 16, v146
	v_ashrrev_i32_e32 v61, 31, v60
	v_lshl_add_u64 v[64:65], v[60:61], 1, v[14:15]
	v_cvt_pk_bf16_f32 v66, v48, v49
	v_cvt_pk_bf16_f32 v67, v50, v51
	ds_write_b64 v238, v[66:67] offset:32
	s_and_saveexec_b64 s[6:7], s[36:37]
	s_cbranch_execz .LBB0_358
	v_lshl_add_u64 v[60:61], v[60:61], 2, v[12:13]
	global_store_dwordx4 v[60:61], v[48:51], off
.LBB0_358:
	s_or_b64 exec, exec, s[6:7]
	s_nop 0
	v_or_b32_e32 v48, 24, v146
	v_ashrrev_i32_e32 v49, 31, v48
	v_lshl_add_u64 v[50:51], v[48:49], 1, v[14:15]
	v_cvt_pk_bf16_f32 v60, v52, v53
	v_cvt_pk_bf16_f32 v61, v54, v55
	ds_write_b64 v238, v[60:61] offset:48
	s_and_saveexec_b64 s[6:7], s[36:37]
	s_cbranch_execz .LBB0_360
	v_lshl_add_u64 v[48:49], v[48:49], 2, v[12:13]
	global_store_dwordx4 v[48:49], v[52:55], off
.LBB0_360:
	s_or_b64 exec, exec, s[6:7]
	v_or_b32_e32 v48, 32, v146
	v_ashrrev_i32_e32 v49, 31, v48
	v_lshl_add_u64 v[50:51], v[48:49], 1, v[14:15]
	v_cvt_pk_bf16_f32 v52, v32, v33
	v_cvt_pk_bf16_f32 v53, v34, v35
	ds_write_b64 v238, v[52:53] offset:64
	s_and_saveexec_b64 s[6:7], s[36:37]
	s_cbranch_execz .LBB0_362
	v_lshl_add_u64 v[48:49], v[48:49], 2, v[12:13]
	global_store_dwordx4 v[48:49], v[32:35], off
.LBB0_362:
	s_or_b64 exec, exec, s[6:7]
	s_nop 0
	v_or_b32_e32 v32, 40, v146
	v_ashrrev_i32_e32 v33, 31, v32
	v_lshl_add_u64 v[34:35], v[32:33], 1, v[14:15]
	v_cvt_pk_bf16_f32 v48, v56, v57
	v_cvt_pk_bf16_f32 v49, v58, v59
	ds_write_b64 v238, v[48:49] offset:80
	s_and_saveexec_b64 s[6:7], s[36:37]
	s_cbranch_execz .LBB0_364
	v_lshl_add_u64 v[32:33], v[32:33], 2, v[12:13]
	global_store_dwordx4 v[32:33], v[56:59], off
.LBB0_364:
	s_or_b64 exec, exec, s[6:7]
	v_or_b32_e32 v32, 48, v146
	v_ashrrev_i32_e32 v33, 31, v32
	v_lshl_add_u64 v[34:35], v[32:33], 1, v[14:15]
	v_cvt_pk_bf16_f32 v48, v36, v37
	v_cvt_pk_bf16_f32 v49, v38, v39
	ds_write_b64 v238, v[48:49] offset:96
	s_and_saveexec_b64 s[6:7], s[36:37]
	s_cbranch_execz .LBB0_366
	v_lshl_add_u64 v[32:33], v[32:33], 2, v[12:13]
	global_store_dwordx4 v[32:33], v[36:39], off
.LBB0_366:
	s_or_b64 exec, exec, s[6:7]
	v_or_b32_e32 v32, 56, v146
	v_ashrrev_i32_e32 v33, 31, v32
	v_lshl_add_u64 v[34:35], v[32:33], 1, v[14:15]
	v_cvt_pk_bf16_f32 v36, v40, v41
	v_cvt_pk_bf16_f32 v37, v42, v43
	ds_write_b64 v238, v[36:37] offset:112
	s_and_saveexec_b64 s[6:7], s[36:37]
	s_cbranch_execz .LBB0_368
	v_lshl_add_u64 v[32:33], v[32:33], 2, v[12:13]
	global_store_dwordx4 v[32:33], v[40:43], off
.LBB0_368:
	s_or_b64 exec, exec, s[6:7]
	v_or_b32_e32 v32, 64, v146
	v_ashrrev_i32_e32 v33, 31, v32
	v_lshl_add_u64 v[34:35], v[32:33], 1, v[14:15]
	v_cvt_pk_bf16_f32 v36, v16, v17
	v_cvt_pk_bf16_f32 v37, v18, v19
	ds_write_b64 v238, v[36:37] offset:128
	s_and_saveexec_b64 s[6:7], s[36:37]
	s_cbranch_execz .LBB0_370
	v_lshl_add_u64 v[32:33], v[32:33], 2, v[12:13]
	global_store_dwordx4 v[32:33], v[16:19], off
.LBB0_370:
	s_or_b64 exec, exec, s[6:7]
	s_nop 0
	v_or_b32_e32 v16, 0x48, v146
	v_ashrrev_i32_e32 v17, 31, v16
	v_lshl_add_u64 v[18:19], v[16:17], 1, v[14:15]
	v_cvt_pk_bf16_f32 v32, v44, v45
	v_cvt_pk_bf16_f32 v33, v46, v47
	ds_write_b64 v238, v[32:33] offset:144
	s_and_saveexec_b64 s[6:7], s[36:37]
	s_cbranch_execz .LBB0_372
	v_lshl_add_u64 v[16:17], v[16:17], 2, v[12:13]
	global_store_dwordx4 v[16:17], v[44:47], off
.LBB0_372:
	s_or_b64 exec, exec, s[6:7]
	v_or_b32_e32 v16, 0x50, v146
	v_ashrrev_i32_e32 v17, 31, v16
	v_lshl_add_u64 v[18:19], v[16:17], 1, v[14:15]
	v_cvt_pk_bf16_f32 v32, v20, v21
	v_cvt_pk_bf16_f32 v33, v22, v23
	ds_write_b64 v238, v[32:33] offset:160
	s_and_saveexec_b64 s[6:7], s[36:37]
	s_cbranch_execz .LBB0_374
	v_lshl_add_u64 v[16:17], v[16:17], 2, v[12:13]
	global_store_dwordx4 v[16:17], v[20:23], off
.LBB0_374:
	s_or_b64 exec, exec, s[6:7]
	v_or_b32_e32 v16, 0x58, v146
	v_ashrrev_i32_e32 v17, 31, v16
	v_lshl_add_u64 v[18:19], v[16:17], 1, v[14:15]
	v_cvt_pk_bf16_f32 v20, v24, v25
	v_cvt_pk_bf16_f32 v21, v26, v27
	ds_write_b64 v238, v[20:21] offset:176
	s_and_saveexec_b64 s[6:7], s[36:37]
	s_cbranch_execz .LBB0_376
	v_lshl_add_u64 v[16:17], v[16:17], 2, v[12:13]
	global_store_dwordx4 v[16:17], v[24:27], off
.LBB0_376:
	s_or_b64 exec, exec, s[6:7]
	v_or_b32_e32 v16, 0x60, v146
	v_ashrrev_i32_e32 v17, 31, v16
	v_lshl_add_u64 v[18:19], v[16:17], 1, v[14:15]
	v_cvt_pk_bf16_f32 v20, v0, v1
	v_cvt_pk_bf16_f32 v21, v2, v3
	ds_write_b64 v238, v[20:21] offset:192
	s_and_saveexec_b64 s[6:7], s[36:37]
	s_cbranch_execz .LBB0_378
	v_lshl_add_u64 v[16:17], v[16:17], 2, v[12:13]
	global_store_dwordx4 v[16:17], v[0:3], off
.LBB0_378:
	s_or_b64 exec, exec, s[6:7]
	s_nop 0
	v_or_b32_e32 v0, 0x68, v146
	v_ashrrev_i32_e32 v1, 31, v0
	v_lshl_add_u64 v[2:3], v[0:1], 1, v[14:15]
	v_cvt_pk_bf16_f32 v16, v28, v29
	v_cvt_pk_bf16_f32 v17, v30, v31
	ds_write_b64 v238, v[16:17] offset:208
	s_and_saveexec_b64 s[6:7], s[36:37]
	s_cbranch_execz .LBB0_380
	v_lshl_add_u64 v[0:1], v[0:1], 2, v[12:13]
	global_store_dwordx4 v[0:1], v[28:31], off
.LBB0_380:
	s_or_b64 exec, exec, s[6:7]
	v_or_b32_e32 v0, 0x70, v146
	v_ashrrev_i32_e32 v1, 31, v0
	v_lshl_add_u64 v[2:3], v[0:1], 1, v[14:15]
	v_cvt_pk_bf16_f32 v16, v4, v5
	v_cvt_pk_bf16_f32 v17, v6, v7
	ds_write_b64 v238, v[16:17] offset:224
	s_and_saveexec_b64 s[6:7], s[36:37]
	s_cbranch_execz .LBB0_382
	v_lshl_add_u64 v[0:1], v[0:1], 2, v[12:13]
	global_store_dwordx4 v[0:1], v[4:7], off
.LBB0_382:
	s_or_b64 exec, exec, s[6:7]
	v_or_b32_e32 v0, 0x78, v146
	v_ashrrev_i32_e32 v1, 31, v0
	v_lshl_add_u64 v[2:3], v[0:1], 1, v[14:15]
	v_cvt_pk_bf16_f32 v4, v8, v9
	v_cvt_pk_bf16_f32 v5, v10, v11
	ds_write_b64 v238, v[4:5] offset:240
	s_waitcnt lgkmcnt(0)
	ds_read_b128 v[230:233], v239
	ds_read_b128 v[234:237], v239 offset:1088
	s_waitcnt lgkmcnt(1)
	global_store_dwordx4 v[244:245], v[230:233], off
	v_lshl_add_u64 v[244:245], v[244:245], 0, v[246:247]
	s_nop 4
	ds_read_b128 v[230:233], v239 offset:2176
	s_waitcnt lgkmcnt(1)
	global_store_dwordx4 v[244:245], v[234:237], off
	v_lshl_add_u64 v[244:245], v[244:245], 0, v[246:247]
	s_nop 4
	ds_read_b128 v[234:237], v239 offset:3264
	s_waitcnt lgkmcnt(1)
	global_store_dwordx4 v[244:245], v[230:233], off
	v_lshl_add_u64 v[244:245], v[244:245], 0, v[246:247]
	s_nop 4
	ds_read_b128 v[230:233], v239 offset:4352
	s_waitcnt lgkmcnt(1)
	global_store_dwordx4 v[244:245], v[234:237], off
	v_lshl_add_u64 v[244:245], v[244:245], 0, v[246:247]
	s_nop 4
	ds_read_b128 v[234:237], v239 offset:5440
	s_waitcnt lgkmcnt(1)
	global_store_dwordx4 v[244:245], v[230:233], off
	v_lshl_add_u64 v[244:245], v[244:245], 0, v[246:247]
	s_nop 4
	ds_read_b128 v[230:233], v239 offset:6528
	s_waitcnt lgkmcnt(1)
	global_store_dwordx4 v[244:245], v[234:237], off
	v_lshl_add_u64 v[244:245], v[244:245], 0, v[246:247]
	s_nop 4
	ds_read_b128 v[234:237], v239 offset:7616
	s_waitcnt lgkmcnt(1)
	global_store_dwordx4 v[244:245], v[230:233], off
	v_lshl_add_u64 v[244:245], v[244:245], 0, v[246:247]
	s_waitcnt lgkmcnt(0)
	global_store_dwordx4 v[244:245], v[234:237], off
	s_and_saveexec_b64 s[6:7], s[36:37]
	s_cbranch_execz .LBB0_384
	v_lshl_add_u64 v[0:1], v[0:1], 2, v[12:13]
	global_store_dwordx4 v[0:1], v[8:11], off

.LBB0_388:
	s_andn2_saveexec_b64 s[0:1], s[4:5]
	s_cbranch_execz .LBB0_392
	v_mov_b64_e32 v[12:13], s[58:59]
	v_mad_i64_i32 v[12:13], s[4:5], v72, s34, v[12:13]
	v_lshl_add_u64 v[12:13], v[128:129], 1, v[12:13]
	v_mov_b32_e32 v77, v129
	v_cvt_pk_bf16_f32 v14, v68, v69
	v_cvt_pk_bf16_f32 v15, v70, v71
	v_lshl_add_u64 v[12:13], v[12:13], 0, v[76:77]
	v_and_b32_e32 v230, 31, v155
	v_bfe_u32 v231, v155, 5, 1
	v_lshrrev_b32_e32 v232, 6, v155
	v_lshrrev_b32_e32 v233, 1, v232
	v_and_b32_e32 v233, v233, v232
	v_lshrrev_b32_e32 v234, 2, v232
	v_and_b32_e32 v233, v233, v234
	v_mul_u32_u24_e32 v232, 0x2200, v232
	v_mul_u32_u24_e32 v233, 0x11200, v233
	v_add_u32_e32 v232, v232, v233
	v_mul_u32_u24_e32 v238, 0x110, v230
	v_add_u32_e32 v238, v238, v232
	v_lshl_add_u32 v238, v231, 3, v238
	v_bfe_u32 v234, v155, 4, 2
	v_and_b32_e32 v235, 15, v155
	v_mul_u32_u24_e32 v239, 0x110, v234
	v_add_u32_e32 v239, v239, v232
	v_lshl_add_u32 v239, v235, 4, v239
	v_sub_u32_e32 v236, v234, v230
	v_mul_i32_i24_e32 v236, 0x300, v236
	v_lshl_add_u32 v236, v235, 4, v236
	v_lshlrev_b32_e32 v237, 3, v231
	v_sub_u32_e32 v246, v236, v237
	v_add_u32_e32 v246, 0xfffffc00, v246
	v_ashrrev_i32_e32 v247, 31, v246
	v_lshl_add_u64 v[244:245], v[12:13], 0, v[246:247]
	v_mov_b32_e32 v246, 0xc00
	v_mov_b32_e32 v247, 0
	ds_write_b64 v238, v[14:15]
	v_cvt_pk_bf16_f32 v14, v64, v65
	v_cvt_pk_bf16_f32 v15, v66, v67
	ds_write_b64 v238, v[14:15] offset:16
	v_cvt_pk_bf16_f32 v14, v48, v49
	v_cvt_pk_bf16_f32 v15, v50, v51
	ds_write_b64 v238, v[14:15] offset:32
	v_cvt_pk_bf16_f32 v14, v52, v53
	v_cvt_pk_bf16_f32 v15, v54, v55
	ds_write_b64 v238, v[14:15] offset:48
	v_cvt_pk_bf16_f32 v14, v32, v33
	v_cvt_pk_bf16_f32 v15, v34, v35
	ds_write_b64 v238, v[14:15] offset:64
	v_cvt_pk_bf16_f32 v14, v56, v57
	v_cvt_pk_bf16_f32 v15, v58, v59
	ds_write_b64 v238, v[14:15] offset:80
	v_cvt_pk_bf16_f32 v14, v36, v37
	v_cvt_pk_bf16_f32 v15, v38, v39
	ds_write_b64 v238, v[14:15] offset:96
	v_cvt_pk_bf16_f32 v14, v40, v41
	v_cvt_pk_bf16_f32 v15, v42, v43
	ds_write_b64 v238, v[14:15] offset:112
	v_cvt_pk_bf16_f32 v14, v16, v17
	v_cvt_pk_bf16_f32 v15, v18, v19
	v_cvt_pk_bf16_f32 v0, v0, v1
	v_cvt_pk_bf16_f32 v1, v2, v3
	ds_write_b64 v238, v[14:15] offset:128
	v_cvt_pk_bf16_f32 v14, v44, v45
	v_cvt_pk_bf16_f32 v15, v46, v47
	ds_write_b64 v238, v[0:1] offset:192
	v_cvt_pk_bf16_f32 v0, v28, v29
	v_cvt_pk_bf16_f32 v1, v30, v31
	ds_write_b64 v238, v[14:15] offset:144
	v_cvt_pk_bf16_f32 v14, v20, v21
	v_cvt_pk_bf16_f32 v15, v22, v23
	ds_write_b64 v238, v[0:1] offset:208
	v_cvt_pk_bf16_f32 v0, v4, v5
	v_cvt_pk_bf16_f32 v1, v6, v7
	ds_write_b64 v238, v[14:15] offset:160
	v_cvt_pk_bf16_f32 v14, v24, v25
	v_cvt_pk_bf16_f32 v15, v26, v27
	ds_write_b64 v238, v[0:1] offset:224
	v_cvt_pk_bf16_f32 v0, v8, v9
	v_cvt_pk_bf16_f32 v1, v10, v11
	ds_write_b64 v238, v[14:15] offset:176
	ds_write_b64 v238, v[0:1] offset:240
	s_waitcnt lgkmcnt(0)
	ds_read_b128 v[230:233], v239
	ds_read_b128 v[234:237], v239 offset:1088
	s_waitcnt lgkmcnt(1)
	global_store_dwordx4 v[244:245], v[230:233], off
	v_lshl_add_u64 v[244:245], v[244:245], 0, v[246:247]
	s_nop 4
	ds_read_b128 v[230:233], v239 offset:2176
	s_waitcnt lgkmcnt(1)
	global_store_dwordx4 v[244:245], v[234:237], off
	v_lshl_add_u64 v[244:245], v[244:245], 0, v[246:247]
	s_nop 4
	ds_read_b128 v[234:237], v239 offset:3264
	s_waitcnt lgkmcnt(1)
	global_store_dwordx4 v[244:245], v[230:233], off
	v_lshl_add_u64 v[244:245], v[244:245], 0, v[246:247]
	s_nop 4
	ds_read_b128 v[230:233], v239 offset:4352
	s_waitcnt lgkmcnt(1)
	global_store_dwordx4 v[244:245], v[234:237], off
	v_lshl_add_u64 v[244:245], v[244:245], 0, v[246:247]
	s_nop 4
	ds_read_b128 v[234:237], v239 offset:5440
	s_waitcnt lgkmcnt(1)
	global_store_dwordx4 v[244:245], v[230:233], off
	v_lshl_add_u64 v[244:245], v[244:245], 0, v[246:247]
	s_nop 4
	ds_read_b128 v[230:233], v239 offset:6528
	s_waitcnt lgkmcnt(1)
	global_store_dwordx4 v[244:245], v[234:237], off
	v_lshl_add_u64 v[244:245], v[244:245], 0, v[246:247]
	s_nop 4
	ds_read_b128 v[234:237], v239 offset:7616
	s_waitcnt lgkmcnt(1)
	global_store_dwordx4 v[244:245], v[230:233], off
	v_lshl_add_u64 v[244:245], v[244:245], 0, v[246:247]
	s_waitcnt lgkmcnt(0)
	global_store_dwordx4 v[244:245], v[234:237], off
	s_and_saveexec_b64 s[4:5], vcc
	s_cbranch_execz .LBB0_391
	v_lshl_add_u64 v[0:1], s[64:65], 0, v[150:151]
	v_lshl_add_u64 v[0:1], v[144:145], 2, v[0:1]
	global_store_dword v[0:1], v62, off offset:128

.LBB0_394:
	v_lshlrev_b64 v[12:13], 10, v[72:73]
	v_lshl_add_u64 v[12:13], s[56:57], 0, v[12:13]
	v_lshl_add_u64 v[12:13], v[152:153], 1, v[12:13]
	v_mov_b32_e32 v77, v129
	v_lshl_add_u64 v[12:13], v[12:13], 0, v[76:77]
	v_cvt_pk_bf16_f32 v14, v68, v69
	v_cvt_pk_bf16_f32 v15, v70, v71
	v_and_b32_e32 v230, 31, v155
	v_bfe_u32 v231, v155, 5, 1
	v_lshrrev_b32_e32 v232, 6, v155
	v_lshrrev_b32_e32 v233, 1, v232
	v_and_b32_e32 v233, v233, v232
	v_lshrrev_b32_e32 v234, 2, v232
	v_and_b32_e32 v233, v233, v234
	v_mul_u32_u24_e32 v232, 0x2200, v232
	v_mul_u32_u24_e32 v233, 0x11200, v233
	v_add_u32_e32 v232, v232, v233
	v_mul_u32_u24_e32 v238, 0x110, v230
	v_add_u32_e32 v238, v238, v232
	v_lshl_add_u32 v238, v231, 3, v238
	v_bfe_u32 v234, v155, 4, 2
	v_and_b32_e32 v235, 15, v155
	v_mul_u32_u24_e32 v239, 0x110, v234
	v_add_u32_e32 v239, v239, v232
	v_lshl_add_u32 v239, v235, 4, v239
	v_sub_u32_e32 v236, v234, v230
	v_mul_i32_i24_e32 v236, 0x400, v236
	v_lshl_add_u32 v236, v235, 4, v236
	v_lshlrev_b32_e32 v237, 3, v231
	v_sub_u32_e32 v246, v236, v237
	v_ashrrev_i32_e32 v247, 31, v246
	v_lshl_add_u64 v[244:245], v[12:13], 0, v[246:247]
	v_mov_b32_e32 v246, 0x1000
	v_mov_b32_e32 v247, 0
	ds_write_b64 v238, v[14:15]
	v_cvt_pk_bf16_f32 v14, v64, v65
	v_cvt_pk_bf16_f32 v15, v66, v67
	ds_write_b64 v238, v[14:15] offset:16
	v_cvt_pk_bf16_f32 v14, v48, v49
	v_cvt_pk_bf16_f32 v15, v50, v51
	ds_write_b64 v238, v[14:15] offset:32
	v_cvt_pk_bf16_f32 v14, v52, v53
	v_cvt_pk_bf16_f32 v15, v54, v55
	ds_write_b64 v238, v[14:15] offset:48
	v_cvt_pk_bf16_f32 v14, v32, v33
	v_cvt_pk_bf16_f32 v15, v34, v35
	ds_write_b64 v238, v[14:15] offset:64
	v_cvt_pk_bf16_f32 v14, v56, v57
	v_cvt_pk_bf16_f32 v15, v58, v59
	ds_write_b64 v238, v[14:15] offset:80
	v_cvt_pk_bf16_f32 v14, v36, v37
	v_cvt_pk_bf16_f32 v15, v38, v39
	ds_write_b64 v238, v[14:15] offset:96
	v_cvt_pk_bf16_f32 v14, v40, v41
	v_cvt_pk_bf16_f32 v15, v42, v43
	ds_write_b64 v238, v[14:15] offset:112
	v_cvt_pk_bf16_f32 v14, v16, v17
	v_cvt_pk_bf16_f32 v15, v18, v19
	v_cvt_pk_bf16_f32 v0, v0, v1
	v_cvt_pk_bf16_f32 v1, v2, v3
	ds_write_b64 v238, v[14:15] offset:128
	v_cvt_pk_bf16_f32 v14, v44, v45
	v_cvt_pk_bf16_f32 v15, v46, v47
	ds_write_b64 v238, v[0:1] offset:192
	v_cvt_pk_bf16_f32 v0, v28, v29
	v_cvt_pk_bf16_f32 v1, v30, v31
	ds_write_b64 v238, v[14:15] offset:144
	v_cvt_pk_bf16_f32 v14, v20, v21
	v_cvt_pk_bf16_f32 v15, v22, v23
	ds_write_b64 v238, v[0:1] offset:208
	v_cvt_pk_bf16_f32 v0, v4, v5
	v_cvt_pk_bf16_f32 v1, v6, v7
	ds_write_b64 v238, v[14:15] offset:160
	v_cvt_pk_bf16_f32 v14, v24, v25
	v_cvt_pk_bf16_f32 v15, v26, v27
	ds_write_b64 v238, v[0:1] offset:224
	v_cvt_pk_bf16_f32 v0, v8, v9
	v_cvt_pk_bf16_f32 v1, v10, v11
	ds_write_b64 v238, v[14:15] offset:176
	ds_write_b64 v238, v[0:1] offset:240
	s_waitcnt lgkmcnt(0)
	ds_read_b128 v[230:233], v239
	ds_read_b128 v[234:237], v239 offset:1088
	s_waitcnt lgkmcnt(1)
	global_store_dwordx4 v[244:245], v[230:233], off
	v_lshl_add_u64 v[244:245], v[244:245], 0, v[246:247]
	s_nop 4
	ds_read_b128 v[230:233], v239 offset:2176
	s_waitcnt lgkmcnt(1)
	global_store_dwordx4 v[244:245], v[234:237], off
	v_lshl_add_u64 v[244:245], v[244:245], 0, v[246:247]
	s_nop 4
	ds_read_b128 v[234:237], v239 offset:3264
	s_waitcnt lgkmcnt(1)
	global_store_dwordx4 v[244:245], v[230:233], off
	v_lshl_add_u64 v[244:245], v[244:245], 0, v[246:247]
	s_nop 4
	ds_read_b128 v[230:233], v239 offset:4352
	s_waitcnt lgkmcnt(1)
	global_store_dwordx4 v[244:245], v[234:237], off
	v_lshl_add_u64 v[244:245], v[244:245], 0, v[246:247]
	s_nop 4
	ds_read_b128 v[234:237], v239 offset:5440
	s_waitcnt lgkmcnt(1)
	global_store_dwordx4 v[244:245], v[230:233], off
	v_lshl_add_u64 v[244:245], v[244:245], 0, v[246:247]
	s_nop 4
	ds_read_b128 v[230:233], v239 offset:6528
	s_waitcnt lgkmcnt(1)
	global_store_dwordx4 v[244:245], v[234:237], off
	v_lshl_add_u64 v[244:245], v[244:245], 0, v[246:247]
	s_nop 4
	ds_read_b128 v[234:237], v239 offset:7616
	s_waitcnt lgkmcnt(1)
	global_store_dwordx4 v[244:245], v[230:233], off
	v_lshl_add_u64 v[244:245], v[244:245], 0, v[246:247]
	s_waitcnt lgkmcnt(0)
	global_store_dwordx4 v[244:245], v[234:237], off
	s_branch .LBB0_276
